# nt hint on the P6 X1B row stores (X1B is re-read only three phases later), on top of all row-store exchanges
# baseline (speedup 1.0000x reference)
.LBB0_1482:
	s_lshr_b32 s17, s46, 4
	s_mul_i32 s48, s17, 0xc00
	s_ashr_i32 s49, s48, 31
	v_lshl_or_b32 v208, s44, 8, v230
	s_lshl_b64 s[48:49], s[48:49], 2
	s_add_u32 s50, s78, s48
	v_ashrrev_i32_e32 v209, 31, v208
	s_addc_u32 s51, s79, s49
	v_lshlrev_b64 v[216:217], 2, v[208:209]
	v_lshl_add_u32 v218, s46, 8, v228
	v_lshl_add_u64 v[112:113], s[50:51], 0, v[216:217]
	s_mov_b64 s[50:51], 0x1502000
	s_mov_b32 s17, 0x1502000
	v_ashrrev_i32_e32 v219, 31, v218
	v_lshl_add_u64 v[114:115], v[112:113], 0, s[50:51]
	v_add_co_u32_e32 v112, vcc, s17, v112
	v_lshl_add_u64 v[220:221], s[52:53], 0, v[216:217]
	v_lshlrev_b64 v[116:117], 12, v[218:219]
	v_addc_co_u32_e32 v113, vcc, 0, v113, vcc
	v_lshl_add_u64 v[144:145], v[220:221], 0, v[116:117]
	global_load_dwordx4 v[224:227], v[144:145], off offset:16
	global_load_dwordx4 v[124:127], v[114:115], off offset:16
	global_load_dwordx4 v[116:119], v[114:115], off offset:512
	global_load_dwordx4 v[240:243], v[144:145], off offset:512
	global_load_dwordx4 v[128:131], v[112:113], off
	global_load_dwordx4 v[244:247], v[144:145], off
	global_load_dwordx4 v[248:251], v[144:145], off offset:528
	s_nop 0
	global_load_dwordx4 v[112:115], v[114:115], off offset:528
	v_or_b32_e32 v210, 16, v218
	v_ashrrev_i32_e32 v211, 31, v210
	v_lshlrev_b64 v[144:145], 12, v[210:211]
	v_or_b32_e32 v214, 32, v218
	v_lshl_add_u64 v[144:145], v[220:221], 0, v[144:145]
	v_ashrrev_i32_e32 v215, 31, v214
	global_load_dwordx4 v[184:187], v[144:145], off offset:16
	global_load_dwordx4 v[188:191], v[144:145], off
	global_load_dwordx4 v[172:175], v[144:145], off offset:528
	global_load_dwordx4 v[176:179], v[144:145], off offset:512
	v_lshlrev_b64 v[144:145], 12, v[214:215]
	v_or_b32_e32 v222, 48, v218
	v_lshl_add_u64 v[144:145], v[220:221], 0, v[144:145]
	v_ashrrev_i32_e32 v223, 31, v222
	global_load_dwordx4 v[168:171], v[144:145], off offset:16
	global_load_dwordx4 v[180:183], v[144:145], off
	global_load_dwordx4 v[160:163], v[144:145], off offset:528
	global_load_dwordx4 v[164:167], v[144:145], off offset:512
	v_lshlrev_b64 v[144:145], 12, v[222:223]
	v_lshl_add_u64 v[148:149], v[220:221], 0, v[144:145]
	global_load_dwordx4 v[152:155], v[148:149], off offset:16
	global_load_dwordx4 v[156:159], v[148:149], off
	global_load_dwordx4 v[144:147], v[148:149], off offset:528
	s_nop 0
	global_load_dwordx4 v[148:151], v[148:149], off offset:512
	v_and_b32_e32 v212, 64, v236
	v_xor_b32_e32 v238, 16, v236
	v_add_u32_e32 v252, 64, v212
	v_cmp_lt_i32_e32 vcc, v238, v252
	v_xor_b32_e32 v239, 32, v236
	v_lshlrev_b64 v[212:213], 11, v[218:219]
	v_cndmask_b32_e32 v238, v236, v238, vcc
	v_lshlrev_b32_e32 v238, 2, v238
	v_cmp_lt_i32_e32 vcc, v239, v252
	v_lshl_add_u64 v[252:253], s[6:7], 0, v[212:213]
	v_lshl_add_u64 v[252:253], v[208:209], 1, v[252:253]
	v_cndmask_b32_e32 v239, v236, v239, vcc
	v_lshlrev_b32_e32 v239, 2, v239
	s_waitcnt vmcnt(0)
	v_pk_fma_f32 v[138:139], v[138:139], v[126:127], v[226:227]
	v_pk_fma_f32 v[136:137], v[136:137], v[124:125], v[224:225]
	v_pk_fma_f32 v[226:227], v[8:9], v[116:117], v[240:241]
	v_pk_fma_f32 v[224:225], v[10:11], v[118:119], v[242:243]
	v_pk_fma_f32 v[140:141], v[140:141], v[128:129], v[244:245]
	v_pk_fma_f32 v[10:11], v[142:143], v[130:131], v[246:247]
	v_pk_fma_f32 v[142:143], v[6:7], v[114:115], v[250:251]
	v_pk_fma_f32 v[6:7], v[4:5], v[112:113], v[248:249]
	v_and_b32_e32 v244, 15, v228
	v_lshrrev_b32_e32 v245, 6, v228
	v_lshl_add_u32 v246, v245, 4, v244
	v_mul_u32_u24_e32 v246, 0x210, v246
	v_lshrrev_b32_e32 v247, 3, v230
	v_lshl_add_u32 v246, v247, 4, v246
	v_add_u32_e32 v240, 0x21000, v246
	v_lshrrev_b32_e32 v247, 5, v230
	v_lshrrev_b32_e32 v248, 5, v236
	v_lshl_add_u32 v247, v247, 2, v248
	v_lshl_add_u32 v248, v245, 4, v247
	v_mul_u32_u24_e32 v248, 0x210, v248
	v_and_b32_e32 v249, 31, v236
	v_lshl_add_u32 v248, v249, 4, v248
	v_add_u32_e32 v241, 0x21000, v248
	v_sub_u32_e32 v250, v247, v244
	v_lshlrev_b32_e32 v250, 11, v250
	v_lshlrev_b32_e32 v249, 3, v249
	v_sub_u32_e32 v249, v249, v230
	v_lshl_add_u32 v242, v249, 1, v250
	v_add_u32_e32 v242, 0x800, v242
	v_ashrrev_i32_e32 v243, 31, v242
	v_mul_f32_e32 v4, v227, v227
	v_mul_f32_e32 v5, v141, v141
	v_fmac_f32_e32 v4, v226, v226
	v_fmac_f32_e32 v5, v140, v140
	v_fmac_f32_e32 v4, v224, v224
	v_fmac_f32_e32 v5, v10, v10
	v_fmac_f32_e32 v4, v225, v225
	v_fmac_f32_e32 v5, v11, v11
	v_fmac_f32_e32 v4, v6, v6
	v_fmac_f32_e32 v5, v136, v136
	v_fmac_f32_e32 v4, v7, v7
	v_fmac_f32_e32 v5, v137, v137
	v_fmac_f32_e32 v4, v142, v142
	v_fmac_f32_e32 v5, v138, v138
	v_fmac_f32_e32 v4, v143, v143
	v_fmac_f32_e32 v5, v139, v139
	v_add_f32_e32 v5, v5, v4
	v_cvt_pk_bf16_f32 v8, v140, v141
	ds_bpermute_b32 v140, v238, v5
	v_cvt_pk_bf16_f32 v9, v10, v11
	v_cvt_pk_bf16_f32 v10, v136, v137
	v_cvt_pk_bf16_f32 v11, v138, v139
	ds_write_b128 v240, v[8:11]
	s_waitcnt lgkmcnt(0)
	v_add_f32_e32 v136, v5, v140
	ds_bpermute_b32 v137, v239, v136
	v_cvt_pk_bf16_f32 v4, v226, v227
	v_cvt_pk_bf16_f32 v5, v224, v225
	v_cvt_pk_bf16_f32 v6, v6, v7
	v_cvt_pk_bf16_f32 v7, v142, v143
	ds_write_b128 v240, v[4:7] offset:256
	v_lshl_add_u64 v[252:253], v[252:253], 0, v[242:243]
	s_waitcnt lgkmcnt(0)
	s_barrier
	ds_read_b128 v[244:247], v241
	ds_read_b128 v[248:251], v241 offset:1056
	s_waitcnt lgkmcnt(0)
	s_barrier
	global_store_dwordx4 v[252:253], v[244:247], off offset:-2048 nt
	global_store_dwordx4 v[252:253], v[248:251], off offset:2048 nt
	s_and_saveexec_b64 s[50:51], s[0:1]
	s_cbranch_execz .LBB0_1484
	s_waitcnt lgkmcnt(0)
	v_add_f32_e32 v136, v136, v137
	ds_write_b32 v231, v136
.LBB0_1484:
	s_or_b64 exec, exec, s[50:51]
	v_pk_fma_f32 v[132:133], v[132:133], v[128:129], v[188:189]
	v_pk_fma_f32 v[120:121], v[120:121], v[116:117], v[176:177]
	v_mul_f32_e32 v140, v133, v133
	v_pk_fma_f32 v[138:139], v[0:1], v[124:125], v[184:185]
	v_cvt_pk_bf16_f32 v0, v132, v133
	v_fmac_f32_e32 v140, v132, v132
	v_pk_fma_f32 v[132:133], v[14:15], v[114:115], v[174:175]
	v_pk_fma_f32 v[14:15], v[12:13], v[112:113], v[172:173]
	v_mul_f32_e32 v12, v121, v121
	v_pk_fma_f32 v[134:135], v[134:135], v[130:131], v[190:191]
	v_pk_fma_f32 v[122:123], v[122:123], v[118:119], v[178:179]
	v_fmac_f32_e32 v12, v120, v120
	v_fmac_f32_e32 v140, v134, v134
	v_fmac_f32_e32 v12, v122, v122
	v_fmac_f32_e32 v140, v135, v135
	v_fmac_f32_e32 v12, v123, v123
	v_fmac_f32_e32 v140, v138, v138
	v_fmac_f32_e32 v12, v14, v14
	s_waitcnt lgkmcnt(0)
	v_pk_fma_f32 v[136:137], v[2:3], v[126:127], v[186:187]
	v_fmac_f32_e32 v140, v139, v139
	v_fmac_f32_e32 v12, v15, v15
	v_fmac_f32_e32 v140, v136, v136
	v_fmac_f32_e32 v12, v132, v132
	v_fmac_f32_e32 v140, v137, v137
	v_fmac_f32_e32 v12, v133, v133
	v_cvt_pk_bf16_f32 v1, v134, v135
	v_cvt_pk_bf16_f32 v2, v138, v139
	v_cvt_pk_bf16_f32 v3, v136, v137
	v_add_f32_e32 v136, v140, v12
	ds_bpermute_b32 v137, v238, v136
	v_lshlrev_b64 v[210:211], 11, v[210:211]
	v_lshl_add_u64 v[12:13], s[6:7], 0, v[210:211]
	v_lshl_add_u64 v[134:135], v[208:209], 1, v[12:13]
	ds_write_b128 v240, v[0:3]
	v_cvt_pk_bf16_f32 v12, v120, v121
	s_waitcnt lgkmcnt(0)
	v_add_f32_e32 v120, v136, v137
	ds_bpermute_b32 v121, v239, v120
	v_cvt_pk_bf16_f32 v13, v122, v123
	v_cvt_pk_bf16_f32 v14, v14, v15
	v_cvt_pk_bf16_f32 v15, v132, v133
	ds_write_b128 v240, v[12:15] offset:256
	v_lshl_add_u64 v[252:253], v[134:135], 0, v[242:243]
	s_waitcnt lgkmcnt(0)
	s_barrier
	ds_read_b128 v[244:247], v241
	ds_read_b128 v[248:251], v241 offset:1056
	s_waitcnt lgkmcnt(0)
	s_barrier
	global_store_dwordx4 v[252:253], v[244:247], off offset:-2048 nt
	global_store_dwordx4 v[252:253], v[248:251], off offset:2048 nt
	s_and_saveexec_b64 s[50:51], s[0:1]
	s_cbranch_execz .LBB0_1486
	s_waitcnt lgkmcnt(0)
	v_add_f32_e32 v120, v120, v121
	ds_write_b32 v231, v120 offset:64
.LBB0_1486:
	s_or_b64 exec, exec, s[50:51]
	v_add_u32_e32 v226, 0x80, v218
	v_ashrrev_i32_e32 v227, 31, v226
	s_waitcnt lgkmcnt(0)
	v_lshlrev_b64 v[120:121], 12, v[226:227]
	v_add_u32_e32 v224, 0x90, v218
	v_lshl_add_u64 v[120:121], v[220:221], 0, v[120:121]
	v_ashrrev_i32_e32 v225, 31, v224
	global_load_dwordx4 v[184:187], v[120:121], off offset:16
	global_load_dwordx4 v[188:191], v[120:121], off
	global_load_dwordx4 v[172:175], v[120:121], off offset:528
	global_load_dwordx4 v[176:179], v[120:121], off offset:512
	v_lshlrev_b64 v[120:121], 12, v[224:225]
	v_lshl_add_u64 v[132:133], v[220:221], 0, v[120:121]
	global_load_dwordx4 v[136:139], v[132:133], off offset:16
	global_load_dwordx4 v[140:143], v[132:133], off
	global_load_dwordx4 v[120:123], v[132:133], off offset:528
	s_nop 0
	global_load_dwordx4 v[132:135], v[132:133], off offset:512
	v_pk_fma_f32 v[108:109], v[108:109], v[128:129], v[180:181]
	v_pk_fma_f32 v[104:105], v[104:105], v[116:117], v[164:165]
	v_mul_f32_e32 v180, v109, v109
	v_pk_fma_f32 v[168:169], v[16:17], v[124:125], v[168:169]
	v_cvt_pk_bf16_f32 v16, v108, v109
	v_fmac_f32_e32 v180, v108, v108
	v_pk_fma_f32 v[108:109], v[26:27], v[114:115], v[162:163]
	v_pk_fma_f32 v[26:27], v[24:25], v[112:113], v[160:161]
	v_mul_f32_e32 v24, v105, v105
	v_pk_fma_f32 v[110:111], v[110:111], v[130:131], v[182:183]
	v_pk_fma_f32 v[106:107], v[106:107], v[118:119], v[166:167]
	v_fmac_f32_e32 v24, v104, v104
	v_fmac_f32_e32 v180, v110, v110
	v_fmac_f32_e32 v24, v106, v106
	v_fmac_f32_e32 v180, v111, v111
	v_fmac_f32_e32 v24, v107, v107
	v_fmac_f32_e32 v180, v168, v168
	v_fmac_f32_e32 v24, v26, v26
	v_pk_fma_f32 v[170:171], v[18:19], v[126:127], v[170:171]
	v_fmac_f32_e32 v180, v169, v169
	v_fmac_f32_e32 v24, v27, v27
	v_fmac_f32_e32 v180, v170, v170
	v_fmac_f32_e32 v24, v108, v108
	v_fmac_f32_e32 v180, v171, v171
	v_fmac_f32_e32 v24, v109, v109
	v_add_f32_e32 v160, v180, v24
	ds_bpermute_b32 v161, v238, v160
	v_lshlrev_b64 v[214:215], 11, v[214:215]
	v_lshl_add_u64 v[24:25], s[6:7], 0, v[214:215]
	v_cvt_pk_bf16_f32 v17, v110, v111
	v_lshl_add_u64 v[110:111], v[208:209], 1, v[24:25]
	v_cvt_pk_bf16_f32 v18, v168, v169
	v_cvt_pk_bf16_f32 v19, v170, v171
	ds_write_b128 v240, v[16:19]
	v_cvt_pk_bf16_f32 v24, v104, v105
	s_waitcnt lgkmcnt(0)
	v_add_f32_e32 v104, v160, v161
	ds_bpermute_b32 v105, v239, v104
	v_cvt_pk_bf16_f32 v25, v106, v107
	v_cvt_pk_bf16_f32 v26, v26, v27
	v_cvt_pk_bf16_f32 v27, v108, v109
	ds_write_b128 v240, v[24:27] offset:256
	v_lshl_add_u64 v[252:253], v[110:111], 0, v[242:243]
	s_waitcnt lgkmcnt(0)
	s_barrier
	ds_read_b128 v[244:247], v241
	ds_read_b128 v[248:251], v241 offset:1056
	s_waitcnt lgkmcnt(0)
	s_barrier
	global_store_dwordx4 v[252:253], v[244:247], off offset:-2048 nt
	global_store_dwordx4 v[252:253], v[248:251], off offset:2048 nt
	s_and_saveexec_b64 s[50:51], s[0:1]
	s_cbranch_execz .LBB0_1488
	s_waitcnt lgkmcnt(0)
	v_add_f32_e32 v104, v104, v105
	ds_write_b32 v231, v104 offset:128
.LBB0_1488:
	s_or_b64 exec, exec, s[50:51]
	v_pk_fma_f32 v[100:101], v[100:101], v[128:129], v[156:157]
	v_pk_fma_f32 v[96:97], v[96:97], v[116:117], v[148:149]
	v_mul_f32_e32 v108, v101, v101
	v_pk_fma_f32 v[106:107], v[20:21], v[124:125], v[152:153]
	v_cvt_pk_bf16_f32 v20, v100, v101
	v_fmac_f32_e32 v108, v100, v100
	v_pk_fma_f32 v[100:101], v[30:31], v[114:115], v[146:147]
	v_pk_fma_f32 v[30:31], v[28:29], v[112:113], v[144:145]
	v_mul_f32_e32 v28, v97, v97
	v_pk_fma_f32 v[102:103], v[102:103], v[130:131], v[158:159]
	v_pk_fma_f32 v[98:99], v[98:99], v[118:119], v[150:151]
	v_fmac_f32_e32 v28, v96, v96
	v_fmac_f32_e32 v108, v102, v102
	v_fmac_f32_e32 v28, v98, v98
	v_fmac_f32_e32 v108, v103, v103
	v_fmac_f32_e32 v28, v99, v99
	v_fmac_f32_e32 v108, v106, v106
	v_fmac_f32_e32 v28, v30, v30
	s_waitcnt lgkmcnt(0)
	v_pk_fma_f32 v[104:105], v[22:23], v[126:127], v[154:155]
	v_fmac_f32_e32 v108, v107, v107
	v_fmac_f32_e32 v28, v31, v31
	v_fmac_f32_e32 v108, v104, v104
	v_fmac_f32_e32 v28, v100, v100
	v_fmac_f32_e32 v108, v105, v105
	v_fmac_f32_e32 v28, v101, v101
	v_cvt_pk_bf16_f32 v21, v102, v103
	v_cvt_pk_bf16_f32 v22, v106, v107
	v_cvt_pk_bf16_f32 v23, v104, v105
	v_add_f32_e32 v104, v108, v28
	ds_bpermute_b32 v105, v238, v104
	v_lshlrev_b64 v[160:161], 11, v[222:223]
	v_lshl_add_u64 v[28:29], s[6:7], 0, v[160:161]
	v_lshl_add_u64 v[102:103], v[208:209], 1, v[28:29]
	ds_write_b128 v240, v[20:23]
	v_cvt_pk_bf16_f32 v28, v96, v97
	s_waitcnt lgkmcnt(0)
	v_add_f32_e32 v96, v104, v105
	ds_bpermute_b32 v97, v239, v96
	v_cvt_pk_bf16_f32 v29, v98, v99
	v_cvt_pk_bf16_f32 v30, v30, v31
	v_cvt_pk_bf16_f32 v31, v100, v101
	ds_write_b128 v240, v[28:31] offset:256
	v_lshl_add_u64 v[252:253], v[102:103], 0, v[242:243]
	s_waitcnt lgkmcnt(0)
	s_barrier
	ds_read_b128 v[244:247], v241
	ds_read_b128 v[248:251], v241 offset:1056
	s_waitcnt lgkmcnt(0)
	s_barrier
	global_store_dwordx4 v[252:253], v[244:247], off offset:-2048 nt
	global_store_dwordx4 v[252:253], v[248:251], off offset:2048 nt
	s_and_saveexec_b64 s[50:51], s[0:1]
	s_cbranch_execz .LBB0_1490
	s_waitcnt lgkmcnt(0)
	v_add_f32_e32 v96, v96, v97
	ds_write_b32 v231, v96 offset:192
.LBB0_1490:
	s_or_b64 exec, exec, s[50:51]
	v_or_b32_e32 v96, 32, v226
	s_waitcnt lgkmcnt(0)
	v_ashrrev_i32_e32 v97, 31, v96
	v_lshlrev_b64 v[96:97], 12, v[96:97]
	v_add_u32_e32 v166, 0xb0, v218
	v_lshl_add_u64 v[96:97], v[220:221], 0, v[96:97]
	v_ashrrev_i32_e32 v167, 31, v166
	global_load_dwordx4 v[152:155], v[96:97], off offset:16
	global_load_dwordx4 v[156:159], v[96:97], off
	global_load_dwordx4 v[144:147], v[96:97], off offset:528
	global_load_dwordx4 v[148:151], v[96:97], off offset:512
	v_lshlrev_b64 v[96:97], 12, v[166:167]
	v_lshl_add_u64 v[100:101], v[220:221], 0, v[96:97]
	global_load_dwordx4 v[104:107], v[100:101], off offset:16
	global_load_dwordx4 v[108:111], v[100:101], off
	global_load_dwordx4 v[96:99], v[100:101], off offset:528
	s_nop 0
	global_load_dwordx4 v[100:103], v[100:101], off offset:512
	s_waitcnt vmcnt(18)
	v_pk_fma_f32 v[92:93], v[92:93], v[128:129], v[188:189]
	s_waitcnt vmcnt(16)
	v_pk_fma_f32 v[88:89], v[88:89], v[116:117], v[176:177]
	v_mul_f32_e32 v170, v93, v93
	v_pk_fma_f32 v[168:169], v[32:33], v[124:125], v[184:185]
	v_cvt_pk_bf16_f32 v32, v92, v93
	v_fmac_f32_e32 v170, v92, v92
	v_pk_fma_f32 v[92:93], v[50:51], v[114:115], v[174:175]
	v_pk_fma_f32 v[50:51], v[48:49], v[112:113], v[172:173]
	v_mul_f32_e32 v48, v89, v89
	v_pk_fma_f32 v[94:95], v[94:95], v[130:131], v[190:191]
	v_pk_fma_f32 v[90:91], v[90:91], v[118:119], v[178:179]
	v_fmac_f32_e32 v48, v88, v88
	v_fmac_f32_e32 v170, v94, v94
	v_fmac_f32_e32 v48, v90, v90
	v_fmac_f32_e32 v170, v95, v95
	v_fmac_f32_e32 v48, v91, v91
	v_fmac_f32_e32 v170, v168, v168
	v_fmac_f32_e32 v48, v50, v50
	v_pk_fma_f32 v[164:165], v[34:35], v[126:127], v[186:187]
	v_fmac_f32_e32 v170, v169, v169
	v_fmac_f32_e32 v48, v51, v51
	v_fmac_f32_e32 v170, v164, v164
	v_fmac_f32_e32 v48, v92, v92
	v_fmac_f32_e32 v170, v165, v165
	v_fmac_f32_e32 v48, v93, v93
	v_cvt_pk_bf16_f32 v33, v94, v95
	v_cvt_pk_bf16_f32 v34, v168, v169
	v_cvt_pk_bf16_f32 v35, v164, v165
	v_add_f32_e32 v164, v170, v48
	ds_bpermute_b32 v165, v238, v164
	v_lshlrev_b64 v[162:163], 11, v[226:227]
	v_lshl_add_u64 v[48:49], s[6:7], 0, v[162:163]
	v_lshl_add_u64 v[94:95], v[208:209], 1, v[48:49]
	ds_write_b128 v240, v[32:35]
	v_cvt_pk_bf16_f32 v48, v88, v89
	s_waitcnt lgkmcnt(0)
	v_add_f32_e32 v88, v164, v165
	ds_bpermute_b32 v89, v239, v88
	v_cvt_pk_bf16_f32 v49, v90, v91
	v_cvt_pk_bf16_f32 v50, v50, v51
	v_cvt_pk_bf16_f32 v51, v92, v93
	ds_write_b128 v240, v[48:51] offset:256
	v_lshl_add_u64 v[252:253], v[94:95], 0, v[242:243]
	s_waitcnt lgkmcnt(0)
	s_barrier
	ds_read_b128 v[244:247], v241
	ds_read_b128 v[248:251], v241 offset:1056
	s_waitcnt lgkmcnt(0)
	s_barrier
	global_store_dwordx4 v[252:253], v[244:247], off offset:-2048 nt
	global_store_dwordx4 v[252:253], v[248:251], off offset:2048 nt
	s_and_saveexec_b64 s[50:51], s[0:1]
	s_cbranch_execz .LBB0_1492
	s_waitcnt lgkmcnt(0)
	v_add_f32_e32 v88, v88, v89
	ds_write_b32 v231, v88 offset:256
.LBB0_1492:
	s_or_b64 exec, exec, s[50:51]
	s_waitcnt vmcnt(16)
	v_pk_fma_f32 v[84:85], v[84:85], v[128:129], v[140:141]
	s_waitcnt vmcnt(14)
	v_pk_fma_f32 v[80:81], v[80:81], v[116:117], v[132:133]
	v_mul_f32_e32 v92, v85, v85
	v_pk_fma_f32 v[90:91], v[44:45], v[124:125], v[136:137]
	v_cvt_pk_bf16_f32 v44, v84, v85
	v_fmac_f32_e32 v92, v84, v84
	v_pk_fma_f32 v[84:85], v[54:55], v[114:115], v[122:123]
	v_pk_fma_f32 v[54:55], v[52:53], v[112:113], v[120:121]
	v_mul_f32_e32 v52, v81, v81
	v_pk_fma_f32 v[86:87], v[86:87], v[130:131], v[142:143]
	v_pk_fma_f32 v[82:83], v[82:83], v[118:119], v[134:135]
	v_fmac_f32_e32 v52, v80, v80
	v_fmac_f32_e32 v92, v86, v86
	v_fmac_f32_e32 v52, v82, v82
	v_fmac_f32_e32 v92, v87, v87
	v_fmac_f32_e32 v52, v83, v83
	v_fmac_f32_e32 v92, v90, v90
	v_fmac_f32_e32 v52, v54, v54
	s_waitcnt lgkmcnt(0)
	v_pk_fma_f32 v[88:89], v[46:47], v[126:127], v[138:139]
	v_fmac_f32_e32 v92, v91, v91
	v_fmac_f32_e32 v52, v55, v55
	v_fmac_f32_e32 v92, v88, v88
	v_fmac_f32_e32 v52, v84, v84
	v_fmac_f32_e32 v92, v89, v89
	v_fmac_f32_e32 v52, v85, v85
	v_cvt_pk_bf16_f32 v45, v86, v87
	v_cvt_pk_bf16_f32 v46, v90, v91
	v_cvt_pk_bf16_f32 v47, v88, v89
	v_add_f32_e32 v88, v92, v52
	ds_bpermute_b32 v89, v238, v88
	v_lshlrev_b64 v[164:165], 11, v[224:225]
	v_lshl_add_u64 v[52:53], s[6:7], 0, v[164:165]
	v_lshl_add_u64 v[86:87], v[208:209], 1, v[52:53]
	ds_write_b128 v240, v[44:47]
	v_cvt_pk_bf16_f32 v52, v80, v81
	s_waitcnt lgkmcnt(0)
	v_add_f32_e32 v80, v88, v89
	ds_bpermute_b32 v81, v239, v80
	v_cvt_pk_bf16_f32 v53, v82, v83
	v_cvt_pk_bf16_f32 v54, v54, v55
	v_cvt_pk_bf16_f32 v55, v84, v85
	ds_write_b128 v240, v[52:55] offset:256
	v_lshl_add_u64 v[252:253], v[86:87], 0, v[242:243]
	s_waitcnt lgkmcnt(0)
	s_barrier
	ds_read_b128 v[244:247], v241
	ds_read_b128 v[248:251], v241 offset:1056
	s_waitcnt lgkmcnt(0)
	s_barrier
	global_store_dwordx4 v[252:253], v[244:247], off offset:-2048 nt
	global_store_dwordx4 v[252:253], v[248:251], off offset:2048 nt
	s_and_saveexec_b64 s[50:51], s[0:1]
	s_cbranch_execz .LBB0_1494
	s_waitcnt lgkmcnt(0)
	v_add_f32_e32 v80, v80, v81
	ds_write_b32 v231, v80 offset:320
.LBB0_1494:
	s_or_b64 exec, exec, s[50:51]
	s_waitcnt vmcnt(10)
	v_pk_fma_f32 v[76:77], v[76:77], v[128:129], v[156:157]
	s_waitcnt vmcnt(8)
	v_pk_fma_f32 v[72:73], v[72:73], v[116:117], v[148:149]
	v_mul_f32_e32 v84, v77, v77
	v_pk_fma_f32 v[82:83], v[56:57], v[124:125], v[152:153]
	v_cvt_pk_bf16_f32 v56, v76, v77
	v_fmac_f32_e32 v84, v76, v76
	v_pk_fma_f32 v[76:77], v[70:71], v[114:115], v[146:147]
	v_pk_fma_f32 v[70:71], v[68:69], v[112:113], v[144:145]
	v_mul_f32_e32 v68, v73, v73
	v_pk_fma_f32 v[78:79], v[78:79], v[130:131], v[158:159]
	v_pk_fma_f32 v[74:75], v[74:75], v[118:119], v[150:151]
	v_fmac_f32_e32 v68, v72, v72
	v_fmac_f32_e32 v84, v78, v78
	v_fmac_f32_e32 v68, v74, v74
	v_fmac_f32_e32 v84, v79, v79
	v_fmac_f32_e32 v68, v75, v75
	s_waitcnt lgkmcnt(0)
	v_lshlrev_b64 v[80:81], 11, v[218:219]
	s_mov_b64 s[50:51], 0x50000
	v_fmac_f32_e32 v84, v82, v82
	v_fmac_f32_e32 v68, v70, v70
	v_lshl_add_u64 v[120:121], v[80:81], 0, s[50:51]
	v_pk_fma_f32 v[80:81], v[58:59], v[126:127], v[154:155]
	v_fmac_f32_e32 v84, v83, v83
	v_fmac_f32_e32 v68, v71, v71
	v_fmac_f32_e32 v84, v80, v80
	v_fmac_f32_e32 v68, v76, v76
	v_fmac_f32_e32 v84, v81, v81
	v_fmac_f32_e32 v68, v77, v77
	v_cvt_pk_bf16_f32 v57, v78, v79
	v_cvt_pk_bf16_f32 v58, v82, v83
	v_cvt_pk_bf16_f32 v59, v80, v81
	v_add_f32_e32 v80, v84, v68
	ds_bpermute_b32 v81, v238, v80
	v_lshl_add_u64 v[68:69], s[6:7], 0, v[120:121]
	v_lshl_add_u64 v[78:79], v[208:209], 1, v[68:69]
	ds_write_b128 v240, v[56:59]
	v_cvt_pk_bf16_f32 v68, v72, v73
	s_waitcnt lgkmcnt(0)
	v_add_f32_e32 v72, v80, v81
	ds_bpermute_b32 v73, v239, v72
	v_cvt_pk_bf16_f32 v69, v74, v75
	v_cvt_pk_bf16_f32 v70, v70, v71
	v_cvt_pk_bf16_f32 v71, v76, v77
	ds_write_b128 v240, v[68:71] offset:256
	v_lshl_add_u64 v[252:253], v[78:79], 0, v[242:243]
	s_waitcnt lgkmcnt(0)
	s_barrier
	ds_read_b128 v[244:247], v241
	ds_read_b128 v[248:251], v241 offset:1056
	s_waitcnt lgkmcnt(0)
	s_barrier
	global_store_dwordx4 v[252:253], v[244:247], off offset:-2048 nt
	global_store_dwordx4 v[252:253], v[248:251], off offset:2048 nt
	s_and_saveexec_b64 s[50:51], s[0:1]
	s_cbranch_execz .LBB0_1496
	s_waitcnt lgkmcnt(0)
	v_add_f32_e32 v72, v72, v73
	ds_write_b32 v231, v72 offset:384
.LBB0_1496:
	s_or_b64 exec, exec, s[50:51]
	s_waitcnt vmcnt(8)
	v_pk_fma_f32 v[64:65], v[64:65], v[128:129], v[108:109]
	s_waitcnt vmcnt(6)
	v_pk_fma_f32 v[40:41], v[40:41], v[116:117], v[100:101]
	v_mul_f32_e32 v76, v65, v65
	v_pk_fma_f32 v[74:75], v[60:61], v[124:125], v[104:105]
	v_cvt_pk_bf16_f32 v60, v64, v65
	v_fmac_f32_e32 v76, v64, v64
	v_pk_fma_f32 v[64:65], v[38:39], v[114:115], v[98:99]
	v_pk_fma_f32 v[38:39], v[36:37], v[112:113], v[96:97]
	v_mul_f32_e32 v36, v41, v41
	v_pk_fma_f32 v[66:67], v[66:67], v[130:131], v[110:111]
	v_pk_fma_f32 v[42:43], v[42:43], v[118:119], v[102:103]
	v_fmac_f32_e32 v36, v40, v40
	v_fmac_f32_e32 v76, v66, v66
	v_fmac_f32_e32 v36, v42, v42
	v_fmac_f32_e32 v76, v67, v67
	v_fmac_f32_e32 v36, v43, v43
	v_fmac_f32_e32 v76, v74, v74
	v_fmac_f32_e32 v36, v38, v38
	s_waitcnt lgkmcnt(0)
	v_pk_fma_f32 v[72:73], v[62:63], v[126:127], v[106:107]
	v_fmac_f32_e32 v76, v75, v75
	v_fmac_f32_e32 v36, v39, v39
	v_fmac_f32_e32 v76, v72, v72
	v_fmac_f32_e32 v36, v64, v64
	v_fmac_f32_e32 v76, v73, v73
	v_fmac_f32_e32 v36, v65, v65
	v_cvt_pk_bf16_f32 v61, v66, v67
	v_cvt_pk_bf16_f32 v62, v74, v75
	v_cvt_pk_bf16_f32 v63, v72, v73
	v_add_f32_e32 v72, v76, v36
	ds_bpermute_b32 v73, v238, v72
	v_lshlrev_b64 v[122:123], 11, v[166:167]
	v_lshl_add_u64 v[36:37], s[6:7], 0, v[122:123]
	v_lshl_add_u64 v[66:67], v[208:209], 1, v[36:37]
	ds_write_b128 v240, v[60:63]
	v_cvt_pk_bf16_f32 v36, v40, v41
	s_waitcnt lgkmcnt(0)
	v_add_f32_e32 v40, v72, v73
	ds_bpermute_b32 v41, v239, v40
	v_cvt_pk_bf16_f32 v37, v42, v43
	v_cvt_pk_bf16_f32 v38, v38, v39
	v_cvt_pk_bf16_f32 v39, v64, v65
	ds_write_b128 v240, v[36:39] offset:256
	v_lshl_add_u64 v[252:253], v[66:67], 0, v[242:243]
	s_waitcnt lgkmcnt(0)
	s_barrier
	ds_read_b128 v[244:247], v241
	ds_read_b128 v[248:251], v241 offset:1056
	s_waitcnt lgkmcnt(0)
	s_barrier
	global_store_dwordx4 v[252:253], v[244:247], off offset:-2048 nt
	global_store_dwordx4 v[252:253], v[248:251], off offset:2048 nt
	s_and_saveexec_b64 s[50:51], s[0:1]
	s_cbranch_execz .LBB0_1498
	s_waitcnt lgkmcnt(0)
	v_add_f32_e32 v40, v40, v41
	ds_write_b32 v231, v40 offset:448
